# v24 + grid-barrier spin loops poll with s_sleep 3 instead of s_sleep 1 (less polling traffic)
# speedup vs baseline: 1.0068x; 1.0068x over previous
.LBB0_69:
	s_sleep 3
	global_load_dword v2, v0, s[0:1] offset:32 sc1
	s_waitcnt vmcnt(0)
	v_and_b32_e32 v2, 0xffff0000, v2
	v_cmp_ne_u32_e32 vcc, v2, v1
	s_or_b64 s[6:7], vcc, s[6:7]
	s_andn2_b64 exec, exec, s[6:7]
	s_cbranch_execnz .LBB0_69

; __device__ __forceinline__ unsigned xb_ld(unsigned* p)              { return __hip_atomic_load(p, __ATOMIC_RELAXED, __HIP_MEMORY_SCOPE_AGENT); }
; __device__ __forceinline__ void xcd_barrier_complete(unsigned* bar, unsigned x, unsigned& nloc, unsigned& nx) {
;     ...
;     for (;;) {
;         sum = 0u; cnt = 0u; mine = 0u;
; #pragma unroll
;         for (unsigned j = 0; j < 16; ++j) { const unsigned c = xb_ld(&bar[XB_XCNT(j)]); sum += c; cnt += (c > 0u) ? 1u : 0u; mine = (j == x) ? c : mine; }
;         if (sum == G) break;
;         __builtin_amdgcn_s_sleep(1);
;         if ((++sp & 255u) == 0u) { if (xb_ld(&bar[XB_TMO])) break; if (sp > XB_SPIN_CAP) { atomicAdd(&bar[XB_TMO], 1u); break; } }
;     }
.LBB0_81:
	global_load_dword v15, v16, s[50:51] offset:1024 sc1
	s_waitcnt lgkmcnt(0)
	global_load_dword v0, v16, s[50:51] offset:1280 sc1
	global_load_dword v1, v16, s[50:51] offset:1536 sc1
	global_load_dword v2, v16, s[50:51] offset:1792 sc1
	global_load_dword v3, v16, s[50:51] offset:2048 sc1
	global_load_dword v4, v16, s[50:51] offset:2304 sc1
	global_load_dword v5, v16, s[50:51] offset:2560 sc1
	global_load_dword v6, v16, s[50:51] offset:2816 sc1
	global_load_dword v7, v16, s[50:51] offset:3072 sc1
	global_load_dword v8, v16, s[50:51] offset:3328 sc1
	global_load_dword v9, v16, s[50:51] offset:3584 sc1
	global_load_dword v10, v16, s[50:51] offset:3840 sc1
	global_load_dword v11, v16, s[6:7] sc1
	global_load_dword v12, v16, s[8:9] sc1
	global_load_dword v13, v16, s[10:11] sc1
	global_load_dword v14, v16, s[12:13] sc1
	s_mov_b64 s[14:15], -1
	s_mov_b64 s[16:17], -1
	s_waitcnt vmcnt(14)
	v_add_u32_e32 v17, v0, v15
	s_waitcnt vmcnt(13)
	v_add_u32_e32 v17, v17, v1
	s_waitcnt vmcnt(12)
	v_add_u32_e32 v17, v17, v2
	s_waitcnt vmcnt(11)
	v_add_u32_e32 v17, v17, v3
	s_waitcnt vmcnt(10)
	v_add_u32_e32 v17, v17, v4
	s_waitcnt vmcnt(9)
	v_add_u32_e32 v17, v17, v5
	s_waitcnt vmcnt(8)
	v_add_u32_e32 v17, v17, v6
	s_waitcnt vmcnt(7)
	v_add_u32_e32 v17, v17, v7
	s_waitcnt vmcnt(6)
	v_add_u32_e32 v17, v17, v8
	s_waitcnt vmcnt(5)
	v_add_u32_e32 v17, v17, v9
	s_waitcnt vmcnt(4)
	v_add_u32_e32 v17, v17, v10
	s_waitcnt vmcnt(3)
	v_add_u32_e32 v17, v17, v11
	s_waitcnt vmcnt(2)
	v_add_u32_e32 v17, v17, v12
	s_waitcnt vmcnt(1)
	v_add_u32_e32 v17, v17, v13
	s_waitcnt vmcnt(0)
	v_add_u32_e32 v17, v17, v14
	v_cmp_eq_u32_e32 vcc, s3, v17
	s_cbranch_vccnz .LBB0_80
	s_and_b32 s14, s20, 0xff
	s_cmp_eq_u32 s14, 0
	s_mov_b64 s[14:15], -1
	s_mov_b64 s[18:19], -1
	s_sleep 3
	s_cbranch_scc0 .LBB0_85
	global_load_dword v17, v16, s[50:51] offset:512 sc1
	s_waitcnt vmcnt(0)
	v_cmp_eq_u32_e32 vcc, 0, v17
	s_cbranch_vccnz .LBB0_87
	s_mov_b64 s[18:19], 0

.LBB0_99:
	s_and_b32 s20, s3, 0xff
	s_mov_b64 s[18:19], -1
	s_cmp_lg_u32 s20, 0
	s_mov_b64 s[22:23], -1
	s_sleep 3
	s_cbranch_scc1 .LBB0_102
	global_load_dword v2, v0, s[50:51] offset:512 sc1
	s_waitcnt vmcnt(0)
	v_cmp_eq_u32_e32 vcc, 0, v2
	s_cbranch_vccnz .LBB0_104
	s_mov_b64 s[22:23], 0
	s_mov_b64 s[20:21], -1

.LBB0_116:
	s_and_b32 s20, s3, 0xff
	s_cmp_lg_u32 s20, 0
	s_mov_b64 s[22:23], -1
	s_sleep 3
	s_cbranch_scc1 .LBB0_119
	global_load_dword v1, v0, s[12:13] sc1
	s_waitcnt vmcnt(0)
	v_cmp_eq_u32_e32 vcc, 0, v1
	s_cbranch_vccnz .LBB0_121
	s_mov_b64 s[22:23], 0
	s_mov_b64 s[20:21], -1

; __device__ __forceinline__ unsigned xb_ld(unsigned* p)              { return __hip_atomic_load(p, __ATOMIC_RELAXED, __HIP_MEMORY_SCOPE_AGENT); }
; __device__ __forceinline__ void xcd_barrier_complete(unsigned* bar, unsigned x, unsigned& nloc, unsigned& nx) {
;     ...
;     for (;;) {
;         sum = 0u; cnt = 0u; mine = 0u;
; #pragma unroll
;         for (unsigned j = 0; j < 16; ++j) { const unsigned c = xb_ld(&bar[XB_XCNT(j)]); sum += c; cnt += (c > 0u) ? 1u : 0u; mine = (j == x) ? c : mine; }
;         if (sum == G) break;
;         __builtin_amdgcn_s_sleep(1);
;         if ((++sp & 255u) == 0u) { if (xb_ld(&bar[XB_TMO])) break; if (sp > XB_SPIN_CAP) { atomicAdd(&bar[XB_TMO], 1u); break; } }
;     }
.LBB0_244:
	global_load_dword v15, v205, s[50:51] offset:1024 sc1
	s_waitcnt lgkmcnt(0)
	global_load_dword v0, v205, s[50:51] offset:1280 sc1
	global_load_dword v1, v205, s[50:51] offset:1536 sc1
	global_load_dword v2, v205, s[50:51] offset:1792 sc1
	global_load_dword v3, v205, s[50:51] offset:2048 sc1
	global_load_dword v4, v205, s[50:51] offset:2304 sc1
	global_load_dword v5, v205, s[50:51] offset:2560 sc1
	global_load_dword v6, v205, s[50:51] offset:2816 sc1
	global_load_dword v7, v205, s[50:51] offset:3072 sc1
	global_load_dword v8, v205, s[50:51] offset:3328 sc1
	global_load_dword v9, v205, s[50:51] offset:3584 sc1
	global_load_dword v10, v205, s[50:51] offset:3840 sc1
	global_load_dword v11, v205, s[60:61] sc1
	global_load_dword v12, v205, s[62:63] sc1
	global_load_dword v13, v205, s[64:65] sc1
	global_load_dword v14, v205, s[66:67] sc1
	s_mov_b64 s[8:9], -1
	s_mov_b64 s[10:11], -1
	s_waitcnt vmcnt(14)
	v_add_u32_e32 v16, v0, v15
	s_waitcnt vmcnt(13)
	v_add_u32_e32 v16, v16, v1
	s_waitcnt vmcnt(12)
	v_add_u32_e32 v16, v16, v2
	s_waitcnt vmcnt(11)
	v_add_u32_e32 v16, v16, v3
	s_waitcnt vmcnt(10)
	v_add_u32_e32 v16, v16, v4
	s_waitcnt vmcnt(9)
	v_add_u32_e32 v16, v16, v5
	s_waitcnt vmcnt(8)
	v_add_u32_e32 v16, v16, v6
	s_waitcnt vmcnt(7)
	v_add_u32_e32 v16, v16, v7
	s_waitcnt vmcnt(6)
	v_add_u32_e32 v16, v16, v8
	s_waitcnt vmcnt(5)
	v_add_u32_e32 v16, v16, v9
	s_waitcnt vmcnt(4)
	v_add_u32_e32 v16, v16, v10
	s_waitcnt vmcnt(3)
	v_add_u32_e32 v16, v16, v11
	s_waitcnt vmcnt(2)
	v_add_u32_e32 v16, v16, v12
	s_waitcnt vmcnt(1)
	v_add_u32_e32 v16, v16, v13
	s_waitcnt vmcnt(0)
	v_add_u32_e32 v16, v16, v14
	v_cmp_eq_u32_e32 vcc, s49, v16
	s_cbranch_vccnz .LBB0_243
	s_and_b32 s8, s21, 0xff
	s_cmp_eq_u32 s8, 0
	s_mov_b64 s[8:9], -1
	s_mov_b64 s[16:17], -1
	s_sleep 3
	s_cbranch_scc0 .LBB0_248
	global_load_dword v16, v205, s[58:59] sc1
	s_waitcnt vmcnt(0)
	v_cmp_eq_u32_e32 vcc, 0, v16
	s_cbranch_vccnz .LBB0_250
	s_mov_b64 s[16:17], 0

.LBB0_262:
	s_and_b32 s22, s21, 0xff
	s_mov_b64 s[40:41], -1
	s_cmp_lg_u32 s22, 0
	s_mov_b64 s[44:45], -1
	s_sleep 3
	s_cbranch_scc1 .LBB0_265
	global_load_dword v0, v205, s[58:59] sc1
	s_waitcnt vmcnt(0)
	v_cmp_eq_u32_e32 vcc, 0, v0
	s_cbranch_vccnz .LBB0_267
	s_mov_b64 s[44:45], 0
	s_mov_b64 s[42:43], -1

.LBB0_457:
	s_and_b32 s22, s21, 0xff
	s_mov_b64 s[42:43], -1
	s_cmp_lg_u32 s22, 0
	s_mov_b64 s[46:47], -1
	s_sleep 3
	s_cbranch_scc1 .LBB0_460
	global_load_dword v0, v205, s[58:59] sc1
	s_waitcnt vmcnt(0)
	v_cmp_eq_u32_e32 vcc, 0, v0
	s_cbranch_vccnz .LBB0_462
	s_mov_b64 s[46:47], 0
	s_mov_b64 s[44:45], -1

.LBB0_539:
	s_and_b32 s22, s21, 0xff
	s_mov_b64 s[44:45], -1
	s_cmp_lg_u32 s22, 0
	s_mov_b64 s[68:69], -1
	s_sleep 3
	s_cbranch_scc1 .LBB0_542
	global_load_dword v0, v205, s[58:59] sc1
	s_waitcnt vmcnt(0)
	v_cmp_eq_u32_e32 vcc, 0, v0
	s_cbranch_vccnz .LBB0_544
	s_mov_b64 s[68:69], 0
	s_mov_b64 s[46:47], -1

; __device__ __forceinline__ unsigned xb_ld(unsigned* p)              { return __hip_atomic_load(p, __ATOMIC_RELAXED, __HIP_MEMORY_SCOPE_AGENT); }
; __device__ __forceinline__ void xcd_barrier_complete(unsigned* bar, unsigned x, unsigned& nloc, unsigned& nx) {
;     ...
;     for (;;) {
;         sum = 0u; cnt = 0u; mine = 0u;
; #pragma unroll
;         for (unsigned j = 0; j < 16; ++j) { const unsigned c = xb_ld(&bar[XB_XCNT(j)]); sum += c; cnt += (c > 0u) ? 1u : 0u; mine = (j == x) ? c : mine; }
;         if (sum == G) break;
;         __builtin_amdgcn_s_sleep(1);
;         if ((++sp & 255u) == 0u) { if (xb_ld(&bar[XB_TMO])) break; if (sp > XB_SPIN_CAP) { atomicAdd(&bar[XB_TMO], 1u); break; } }
;     }
.LBB0_618:
	global_load_dword v15, v205, s[50:51] offset:1024 sc1
	s_waitcnt lgkmcnt(0)
	global_load_dword v0, v205, s[50:51] offset:1280 sc1
	global_load_dword v1, v205, s[50:51] offset:1536 sc1
	global_load_dword v2, v205, s[50:51] offset:1792 sc1
	global_load_dword v3, v205, s[50:51] offset:2048 sc1
	global_load_dword v4, v205, s[50:51] offset:2304 sc1
	global_load_dword v5, v205, s[50:51] offset:2560 sc1
	global_load_dword v6, v205, s[50:51] offset:2816 sc1
	global_load_dword v7, v205, s[50:51] offset:3072 sc1
	global_load_dword v8, v205, s[50:51] offset:3328 sc1
	global_load_dword v9, v205, s[50:51] offset:3584 sc1
	global_load_dword v10, v205, s[50:51] offset:3840 sc1
	global_load_dword v11, v205, s[60:61] sc1
	global_load_dword v12, v205, s[62:63] sc1
	global_load_dword v13, v205, s[64:65] sc1
	global_load_dword v14, v205, s[66:67] sc1
	s_mov_b64 s[8:9], -1
	s_mov_b64 s[10:11], -1
	s_waitcnt vmcnt(14)
	v_add_u32_e32 v16, v0, v15
	s_waitcnt vmcnt(13)
	v_add_u32_e32 v16, v16, v1
	s_waitcnt vmcnt(12)
	v_add_u32_e32 v16, v16, v2
	s_waitcnt vmcnt(11)
	v_add_u32_e32 v16, v16, v3
	s_waitcnt vmcnt(10)
	v_add_u32_e32 v16, v16, v4
	s_waitcnt vmcnt(9)
	v_add_u32_e32 v16, v16, v5
	s_waitcnt vmcnt(8)
	v_add_u32_e32 v16, v16, v6
	s_waitcnt vmcnt(7)
	v_add_u32_e32 v16, v16, v7
	s_waitcnt vmcnt(6)
	v_add_u32_e32 v16, v16, v8
	s_waitcnt vmcnt(5)
	v_add_u32_e32 v16, v16, v9
	s_waitcnt vmcnt(4)
	v_add_u32_e32 v16, v16, v10
	s_waitcnt vmcnt(3)
	v_add_u32_e32 v16, v16, v11
	s_waitcnt vmcnt(2)
	v_add_u32_e32 v16, v16, v12
	s_waitcnt vmcnt(1)
	v_add_u32_e32 v16, v16, v13
	s_waitcnt vmcnt(0)
	v_add_u32_e32 v16, v16, v14
	v_cmp_eq_u32_e32 vcc, s49, v16
	s_cbranch_vccnz .LBB0_617
	s_and_b32 s8, s20, 0xff
	s_cmp_eq_u32 s8, 0
	s_mov_b64 s[8:9], -1
	s_mov_b64 s[16:17], -1
	s_sleep 3
	s_cbranch_scc0 .LBB0_622
	global_load_dword v16, v205, s[58:59] sc1
	s_waitcnt vmcnt(0)
	v_cmp_eq_u32_e32 vcc, 0, v16
	s_cbranch_vccnz .LBB0_624
	s_mov_b64 s[16:17], 0

.LBB0_636:
	s_and_b32 s21, s20, 0xff
	s_mov_b64 s[44:45], -1
	s_cmp_lg_u32 s21, 0
	s_mov_b64 s[68:69], -1
	s_sleep 3
	s_cbranch_scc1 .LBB0_639
	global_load_dword v0, v205, s[58:59] sc1
	s_waitcnt vmcnt(0)
	v_cmp_eq_u32_e32 vcc, 0, v0
	s_cbranch_vccnz .LBB0_641
	s_mov_b64 s[68:69], 0
	s_mov_b64 s[46:47], -1

.LBB0_754:
	s_and_b32 s21, s20, 0xff
	s_mov_b64 s[42:43], -1
	s_cmp_lg_u32 s21, 0
	s_mov_b64 s[46:47], -1
	s_sleep 3
	s_cbranch_scc1 .LBB0_757
	global_load_dword v0, v205, s[58:59] sc1
	s_waitcnt vmcnt(0)
	v_cmp_eq_u32_e32 vcc, 0, v0
	s_cbranch_vccnz .LBB0_759
	s_mov_b64 s[46:47], 0
	s_mov_b64 s[44:45], -1

.LBB0_808:
	s_and_b32 s21, s20, 0xff
	s_mov_b64 s[40:41], -1
	s_cmp_lg_u32 s21, 0
	s_mov_b64 s[44:45], -1
	s_sleep 3
	s_cbranch_scc1 .LBB0_811
	global_load_dword v0, v205, s[58:59] sc1
	s_waitcnt vmcnt(0)
	v_cmp_eq_u32_e32 vcc, 0, v0
	s_cbranch_vccnz .LBB0_813
	s_mov_b64 s[44:45], 0
	s_mov_b64 s[42:43], -1

; __device__ __forceinline__ unsigned xb_ld(unsigned* p)              { return __hip_atomic_load(p, __ATOMIC_RELAXED, __HIP_MEMORY_SCOPE_AGENT); }
; __device__ __forceinline__ void xcd_barrier_complete(unsigned* bar, unsigned x, unsigned& nloc, unsigned& nx) {
;     ...
;     for (;;) {
;         sum = 0u; cnt = 0u; mine = 0u;
; #pragma unroll
;         for (unsigned j = 0; j < 16; ++j) { const unsigned c = xb_ld(&bar[XB_XCNT(j)]); sum += c; cnt += (c > 0u) ? 1u : 0u; mine = (j == x) ? c : mine; }
;         if (sum == G) break;
;         __builtin_amdgcn_s_sleep(1);
;         if ((++sp & 255u) == 0u) { if (xb_ld(&bar[XB_TMO])) break; if (sp > XB_SPIN_CAP) { atomicAdd(&bar[XB_TMO], 1u); break; } }
;     }
.LBB0_825:
	global_load_dword v15, v205, s[50:51] offset:1024 sc1
	s_waitcnt lgkmcnt(0)
	global_load_dword v0, v205, s[50:51] offset:1280 sc1
	global_load_dword v1, v205, s[50:51] offset:1536 sc1
	global_load_dword v2, v205, s[50:51] offset:1792 sc1
	global_load_dword v3, v205, s[50:51] offset:2048 sc1
	global_load_dword v4, v205, s[50:51] offset:2304 sc1
	global_load_dword v5, v205, s[50:51] offset:2560 sc1
	global_load_dword v6, v205, s[50:51] offset:2816 sc1
	global_load_dword v7, v205, s[50:51] offset:3072 sc1
	global_load_dword v8, v205, s[50:51] offset:3328 sc1
	global_load_dword v9, v205, s[50:51] offset:3584 sc1
	global_load_dword v10, v205, s[50:51] offset:3840 sc1
	global_load_dword v11, v205, s[60:61] sc1
	global_load_dword v12, v205, s[62:63] sc1
	global_load_dword v13, v205, s[64:65] sc1
	global_load_dword v14, v205, s[66:67] sc1
	s_mov_b64 s[6:7], -1
	s_mov_b64 s[8:9], -1
	s_waitcnt vmcnt(14)
	v_add_u32_e32 v16, v0, v15
	s_waitcnt vmcnt(13)
	v_add_u32_e32 v16, v16, v1
	s_waitcnt vmcnt(12)
	v_add_u32_e32 v16, v16, v2
	s_waitcnt vmcnt(11)
	v_add_u32_e32 v16, v16, v3
	s_waitcnt vmcnt(10)
	v_add_u32_e32 v16, v16, v4
	s_waitcnt vmcnt(9)
	v_add_u32_e32 v16, v16, v5
	s_waitcnt vmcnt(8)
	v_add_u32_e32 v16, v16, v6
	s_waitcnt vmcnt(7)
	v_add_u32_e32 v16, v16, v7
	s_waitcnt vmcnt(6)
	v_add_u32_e32 v16, v16, v8
	s_waitcnt vmcnt(5)
	v_add_u32_e32 v16, v16, v9
	s_waitcnt vmcnt(4)
	v_add_u32_e32 v16, v16, v10
	s_waitcnt vmcnt(3)
	v_add_u32_e32 v16, v16, v11
	s_waitcnt vmcnt(2)
	v_add_u32_e32 v16, v16, v12
	s_waitcnt vmcnt(1)
	v_add_u32_e32 v16, v16, v13
	s_waitcnt vmcnt(0)
	v_add_u32_e32 v16, v16, v14
	v_cmp_eq_u32_e32 vcc, s49, v16
	s_cbranch_vccnz .LBB0_824
	s_and_b32 s6, s16, 0xff
	s_cmp_eq_u32 s6, 0
	s_mov_b64 s[6:7], -1
	s_mov_b64 s[10:11], -1
	s_sleep 3
	s_cbranch_scc0 .LBB0_829
	global_load_dword v16, v205, s[58:59] sc1
	s_waitcnt vmcnt(0)
	v_cmp_eq_u32_e32 vcc, 0, v16
	s_cbranch_vccnz .LBB0_831
	s_mov_b64 s[10:11], 0

.LBB0_843:
	s_and_b32 s21, s20, 0xff
	s_mov_b64 s[38:39], -1
	s_cmp_lg_u32 s21, 0
	s_mov_b64 s[42:43], -1
	s_sleep 3
	s_cbranch_scc1 .LBB0_846
	global_load_dword v0, v205, s[58:59] sc1
	s_waitcnt vmcnt(0)
	v_cmp_eq_u32_e32 vcc, 0, v0
	s_cbranch_vccnz .LBB0_848
	s_mov_b64 s[42:43], 0
	s_mov_b64 s[40:41], -1
